# EpiQkv epilogue hand-written: rope rows fetched 3 rows ahead, batched shuffles
# baseline (speedup 1.0000x reference)
.LBB0_2154:
	s_mov_b32 s98, 0
	s_cmp_eq_u32 s36, s57
	s_cbranch_scc1 .Lqkv_fast
	s_movk_i32 s98, 0x400
	s_cmp_eq_u32 s36, s56
	s_cbranch_scc1 .Lqkv_fast
	s_movk_i32 s98, 0x800
	s_cmp_eq_u32 s36, s55
	s_cbranch_scc1 .Lqkv_fast
	s_movk_i32 s98, 0xc00
	s_cmp_eq_u32 s36, s54
	s_cbranch_scc0 .Lqkv_slow
.Lqkv_fast:
	v_add_u32_e32 v150, s98, v171
	ds_read_b32 v130, v150
	ds_read_b32 v131, v150 offset:64
	ds_read_b32 v132, v150 offset:128
	ds_read_b32 v133, v150 offset:192
	ds_read_b32 v134, v150 offset:512
	ds_read_b32 v135, v150 offset:576
	ds_read_b32 v136, v150 offset:640
	ds_read_b32 v137, v150 offset:704
	s_ashr_i32 s42, s10, 2
	s_cmp_lt_i32 s42, 2
	s_cselect_b64 s[44:45], -1, 0
	s_and_b64 s[40:41], s[24:25], s[44:45]
	s_and_b64 s[38:39], s[40:41], s[2:3]
	s_ashr_i32 s43, s42, 31
	s_lshl_b64 s[42:43], s[42:43], 26
	s_add_u32 s42, s12, s42
	s_addc_u32 s43, s13, s43
	s_lshl_b32 s11, s10, 8
	s_and_b32 s11, s11, 0x300
	v_lshl_add_u32 v151, s36, 8, v168
	v_or_b32_e32 v112, s11, v170
	v_lshlrev_b32_e32 v112, 1, v112
	v_lshl_add_u32 v112, v151, 11, v112
	v_lshlrev_b32_e32 v211, 6, v151
	v_and_b32_e32 v211, 0x1f3c0, v211
	s_cmp_lt_u32 s10, 4
	s_cselect_b64 vcc, -1, 0
	v_mov_b32_e32 v210, 1.0
	s_nop 0
	v_cndmask_b32_e32 v210, v210, v226, vcc
	s_cmp_eq_u64 s[38:39], 0
	s_cbranch_scc1 .Lqkv_plain
	v_mov_b32_e32 v209, 1.0
	v_mov_b32_e32 v150, -1.0
	v_cndmask_b32_e64 v209, v209, v150, s[4:5]
	v_and_b32_e32 v150, 64, v220
	v_xor_b32_e32 v208, 16, v220
	v_add_u32_e32 v150, 64, v150
	v_cmp_lt_i32_e32 vcc, v208, v150
	s_nop 1
	v_cndmask_b32_e32 v208, v220, v208, vcc
	v_lshlrev_b32_e32 v208, 2, v208
	v_mov_b32_e32 v152, 1.0
	v_mov_b32_e32 v153, 1.0
	v_mov_b32_e32 v154, 1.0
	v_mov_b32_e32 v155, 1.0
	v_mov_b32_e32 v156, 1.0
	v_mov_b32_e32 v157, 1.0
	v_mov_b32_e32 v158, 1.0
	v_mov_b32_e32 v159, 1.0
	v_mov_b32_e32 v160, 0
	v_mov_b32_e32 v161, 0
	v_mov_b32_e32 v162, 0
	v_mov_b32_e32 v163, 0
	v_mov_b32_e32 v164, 0
	v_mov_b32_e32 v165, 0
	v_mov_b32_e32 v166, 0
	v_mov_b32_e32 v167, 0
	s_and_saveexec_b64 s[40:41], s[38:39]
	global_load_dwordx4 v[152:155], v211, s[20:21]
	global_load_dwordx4 v[156:159], v211, s[20:21] offset:16
	global_load_dwordx4 v[160:163], v211, s[20:21] offset:32
	global_load_dwordx4 v[164:167], v211, s[20:21] offset:48
	s_or_b64 exec, exec, s[40:41]
	v_mov_b32_e32 v174, 1.0
	v_mov_b32_e32 v175, 1.0
	v_mov_b32_e32 v176, 1.0
	v_mov_b32_e32 v177, 1.0
	v_mov_b32_e32 v178, 1.0
	v_mov_b32_e32 v179, 1.0
	v_mov_b32_e32 v180, 1.0
	v_mov_b32_e32 v181, 1.0
	v_mov_b32_e32 v182, 0
	v_mov_b32_e32 v183, 0
	v_mov_b32_e32 v184, 0
	v_mov_b32_e32 v185, 0
	v_mov_b32_e32 v186, 0
	v_mov_b32_e32 v187, 0
	v_mov_b32_e32 v188, 0
	v_mov_b32_e32 v189, 0
	v_add_u32_e32 v151, 0x400, v211
	s_and_saveexec_b64 s[40:41], s[38:39]
	global_load_dwordx4 v[174:177], v151, s[20:21]
	global_load_dwordx4 v[178:181], v151, s[20:21] offset:16
	global_load_dwordx4 v[182:185], v151, s[20:21] offset:32
	global_load_dwordx4 v[186:189], v151, s[20:21] offset:48
	s_or_b64 exec, exec, s[40:41]
	v_mov_b32_e32 v228, 1.0
	v_mov_b32_e32 v229, 1.0
	v_mov_b32_e32 v230, 1.0
	v_mov_b32_e32 v231, 1.0
	v_mov_b32_e32 v232, 1.0
	v_mov_b32_e32 v233, 1.0
	v_mov_b32_e32 v234, 1.0
	v_mov_b32_e32 v235, 1.0
	v_mov_b32_e32 v236, 0
	v_mov_b32_e32 v237, 0
	v_mov_b32_e32 v238, 0
	v_mov_b32_e32 v239, 0
	v_mov_b32_e32 v240, 0
	v_mov_b32_e32 v241, 0
	v_mov_b32_e32 v242, 0
	v_mov_b32_e32 v243, 0
	v_add_u32_e32 v151, 0x800, v211
	s_and_saveexec_b64 s[40:41], s[38:39]
	global_load_dwordx4 v[228:231], v151, s[20:21]
	global_load_dwordx4 v[232:235], v151, s[20:21] offset:16
	global_load_dwordx4 v[236:239], v151, s[20:21] offset:32
	global_load_dwordx4 v[240:243], v151, s[20:21] offset:48
	s_or_b64 exec, exec, s[40:41]
	s_waitcnt lgkmcnt(0)
	s_waitcnt vmcnt(8)
	v_mul_f32_e32 v160, v209, v160
	v_mul_f32_e32 v161, v209, v161
	v_mul_f32_e32 v162, v209, v162
	v_mul_f32_e32 v163, v209, v163
	v_mul_f32_e32 v164, v209, v164
	v_mul_f32_e32 v165, v209, v165
	v_mul_f32_e32 v166, v209, v166
	v_mul_f32_e32 v167, v209, v167
	v_mul_f32_e32 v126, v126, v130
	v_mul_f32_e32 v127, v127, v130
	v_mul_f32_e32 v128, v128, v130
	v_mul_f32_e32 v129, v129, v130
	v_mul_f32_e32 v122, v122, v130
	v_mul_f32_e32 v123, v123, v130
	v_mul_f32_e32 v124, v124, v130
	v_mul_f32_e32 v125, v125, v130
	v_mul_f32_e32 v118, v118, v130
	v_mul_f32_e32 v119, v119, v130
	v_mul_f32_e32 v120, v120, v130
	v_mul_f32_e32 v121, v121, v130
	v_mul_f32_e32 v114, v114, v130
	v_mul_f32_e32 v115, v115, v130
	v_mul_f32_e32 v116, v116, v130
	v_mul_f32_e32 v117, v117, v130
	ds_bpermute_b32 v244, v208, v126
	ds_bpermute_b32 v245, v208, v127
	ds_bpermute_b32 v246, v208, v128
	ds_bpermute_b32 v247, v208, v129
	ds_bpermute_b32 v248, v208, v122
	ds_bpermute_b32 v249, v208, v123
	ds_bpermute_b32 v250, v208, v124
	ds_bpermute_b32 v251, v208, v125
	s_waitcnt lgkmcnt(0)
	v_mul_f32_e32 v244, v160, v244
	v_mul_f32_e32 v245, v161, v245
	v_mul_f32_e32 v246, v162, v246
	v_mul_f32_e32 v247, v163, v247
	v_mul_f32_e32 v248, v164, v248
	v_mul_f32_e32 v249, v165, v249
	v_mul_f32_e32 v250, v166, v250
	v_mul_f32_e32 v251, v167, v251
	v_fma_f32 v126, v126, v152, v244
	v_fma_f32 v127, v127, v153, v245
	v_fma_f32 v128, v128, v154, v246
	v_fma_f32 v129, v129, v155, v247
	v_fma_f32 v122, v122, v156, v248
	v_fma_f32 v123, v123, v157, v249
	v_fma_f32 v124, v124, v158, v250
	v_fma_f32 v125, v125, v159, v251
	v_mul_f32_e32 v126, v210, v126
	v_mul_f32_e32 v127, v210, v127
	v_mul_f32_e32 v128, v210, v128
	v_mul_f32_e32 v129, v210, v129
	v_mul_f32_e32 v122, v210, v122
	v_mul_f32_e32 v123, v210, v123
	v_mul_f32_e32 v124, v210, v124
	v_mul_f32_e32 v125, v210, v125
	v_cvt_pk_bf16_f32 v244, v126, v127
	v_cvt_pk_bf16_f32 v245, v128, v129
	v_cvt_pk_bf16_f32 v246, v122, v123
	v_cvt_pk_bf16_f32 v247, v124, v125
	global_store_dwordx4 v112, v[244:247], s[42:43]
	s_nop 1
	ds_bpermute_b32 v244, v208, v118
	ds_bpermute_b32 v245, v208, v119
	ds_bpermute_b32 v246, v208, v120
	ds_bpermute_b32 v247, v208, v121
	ds_bpermute_b32 v248, v208, v114
	ds_bpermute_b32 v249, v208, v115
	ds_bpermute_b32 v250, v208, v116
	ds_bpermute_b32 v251, v208, v117
	s_waitcnt lgkmcnt(0)
	v_mul_f32_e32 v244, v160, v244
	v_mul_f32_e32 v245, v161, v245
	v_mul_f32_e32 v246, v162, v246
	v_mul_f32_e32 v247, v163, v247
	v_mul_f32_e32 v248, v164, v248
	v_mul_f32_e32 v249, v165, v249
	v_mul_f32_e32 v250, v166, v250
	v_mul_f32_e32 v251, v167, v251
	v_fma_f32 v118, v118, v152, v244
	v_fma_f32 v119, v119, v153, v245
	v_fma_f32 v120, v120, v154, v246
	v_fma_f32 v121, v121, v155, v247
	v_fma_f32 v114, v114, v156, v248
	v_fma_f32 v115, v115, v157, v249
	v_fma_f32 v116, v116, v158, v250
	v_fma_f32 v117, v117, v159, v251
	v_mul_f32_e32 v118, v210, v118
	v_mul_f32_e32 v119, v210, v119
	v_mul_f32_e32 v120, v210, v120
	v_mul_f32_e32 v121, v210, v121
	v_mul_f32_e32 v114, v210, v114
	v_mul_f32_e32 v115, v210, v115
	v_mul_f32_e32 v116, v210, v116
	v_mul_f32_e32 v117, v210, v117
	v_cvt_pk_bf16_f32 v244, v118, v119
	v_cvt_pk_bf16_f32 v245, v120, v121
	v_cvt_pk_bf16_f32 v246, v114, v115
	v_cvt_pk_bf16_f32 v247, v116, v117
	global_store_dwordx4 v112, v[244:247], s[42:43] offset:256
	v_mov_b32_e32 v152, 1.0
	v_mov_b32_e32 v153, 1.0
	v_mov_b32_e32 v154, 1.0
	v_mov_b32_e32 v155, 1.0
	v_mov_b32_e32 v156, 1.0
	v_mov_b32_e32 v157, 1.0
	v_mov_b32_e32 v158, 1.0
	v_mov_b32_e32 v159, 1.0
	v_mov_b32_e32 v160, 0
	v_mov_b32_e32 v161, 0
	v_mov_b32_e32 v162, 0
	v_mov_b32_e32 v163, 0
	v_mov_b32_e32 v164, 0
	v_mov_b32_e32 v165, 0
	v_mov_b32_e32 v166, 0
	v_mov_b32_e32 v167, 0
	v_add_u32_e32 v151, 0xc00, v211
	s_and_saveexec_b64 s[40:41], s[38:39]
	global_load_dwordx4 v[152:155], v151, s[20:21]
	global_load_dwordx4 v[156:159], v151, s[20:21] offset:16
	global_load_dwordx4 v[160:163], v151, s[20:21] offset:32
	global_load_dwordx4 v[164:167], v151, s[20:21] offset:48
	s_or_b64 exec, exec, s[40:41]
	s_waitcnt vmcnt(10)
	v_mul_f32_e32 v182, v209, v182
	v_mul_f32_e32 v183, v209, v183
	v_mul_f32_e32 v184, v209, v184
	v_mul_f32_e32 v185, v209, v185
	v_mul_f32_e32 v186, v209, v186
	v_mul_f32_e32 v187, v209, v187
	v_mul_f32_e32 v188, v209, v188
	v_mul_f32_e32 v189, v209, v189
	v_mul_f32_e32 v108, v108, v131
	v_mul_f32_e32 v109, v109, v131
	v_mul_f32_e32 v110, v110, v131
	v_mul_f32_e32 v111, v111, v131
	v_mul_f32_e32 v104, v104, v131
	v_mul_f32_e32 v105, v105, v131
	v_mul_f32_e32 v106, v106, v131
	v_mul_f32_e32 v107, v107, v131
	v_mul_f32_e32 v100, v100, v131
	v_mul_f32_e32 v101, v101, v131
	v_mul_f32_e32 v102, v102, v131
	v_mul_f32_e32 v103, v103, v131
	v_mul_f32_e32 v96, v96, v131
	v_mul_f32_e32 v97, v97, v131
	v_mul_f32_e32 v98, v98, v131
	v_mul_f32_e32 v99, v99, v131
	ds_bpermute_b32 v244, v208, v108
	ds_bpermute_b32 v245, v208, v109
	ds_bpermute_b32 v246, v208, v110
	ds_bpermute_b32 v247, v208, v111
	ds_bpermute_b32 v248, v208, v104
	ds_bpermute_b32 v249, v208, v105
	ds_bpermute_b32 v250, v208, v106
	ds_bpermute_b32 v251, v208, v107
	s_waitcnt lgkmcnt(0)
	v_mul_f32_e32 v244, v182, v244
	v_mul_f32_e32 v245, v183, v245
	v_mul_f32_e32 v246, v184, v246
	v_mul_f32_e32 v247, v185, v247
	v_mul_f32_e32 v248, v186, v248
	v_mul_f32_e32 v249, v187, v249
	v_mul_f32_e32 v250, v188, v250
	v_mul_f32_e32 v251, v189, v251
	v_fma_f32 v108, v108, v174, v244
	v_fma_f32 v109, v109, v175, v245
	v_fma_f32 v110, v110, v176, v246
	v_fma_f32 v111, v111, v177, v247
	v_fma_f32 v104, v104, v178, v248
	v_fma_f32 v105, v105, v179, v249
	v_fma_f32 v106, v106, v180, v250
	v_fma_f32 v107, v107, v181, v251
	v_mul_f32_e32 v108, v210, v108
	v_mul_f32_e32 v109, v210, v109
	v_mul_f32_e32 v110, v210, v110
	v_mul_f32_e32 v111, v210, v111
	v_mul_f32_e32 v104, v210, v104
	v_mul_f32_e32 v105, v210, v105
	v_mul_f32_e32 v106, v210, v106
	v_mul_f32_e32 v107, v210, v107
	v_cvt_pk_bf16_f32 v244, v108, v109
	v_cvt_pk_bf16_f32 v245, v110, v111
	v_cvt_pk_bf16_f32 v246, v104, v105
	v_cvt_pk_bf16_f32 v247, v106, v107
	v_add_u32_e32 v150, 0x8000, v112
	global_store_dwordx4 v150, v[244:247], s[42:43]
	s_nop 1
	ds_bpermute_b32 v244, v208, v100
	ds_bpermute_b32 v245, v208, v101
	ds_bpermute_b32 v246, v208, v102
	ds_bpermute_b32 v247, v208, v103
	ds_bpermute_b32 v248, v208, v96
	ds_bpermute_b32 v249, v208, v97
	ds_bpermute_b32 v250, v208, v98
	ds_bpermute_b32 v251, v208, v99
	s_waitcnt lgkmcnt(0)
	v_mul_f32_e32 v244, v182, v244
	v_mul_f32_e32 v245, v183, v245
	v_mul_f32_e32 v246, v184, v246
	v_mul_f32_e32 v247, v185, v247
	v_mul_f32_e32 v248, v186, v248
	v_mul_f32_e32 v249, v187, v249
	v_mul_f32_e32 v250, v188, v250
	v_mul_f32_e32 v251, v189, v251
	v_fma_f32 v100, v100, v174, v244
	v_fma_f32 v101, v101, v175, v245
	v_fma_f32 v102, v102, v176, v246
	v_fma_f32 v103, v103, v177, v247
	v_fma_f32 v96, v96, v178, v248
	v_fma_f32 v97, v97, v179, v249
	v_fma_f32 v98, v98, v180, v250
	v_fma_f32 v99, v99, v181, v251
	v_mul_f32_e32 v100, v210, v100
	v_mul_f32_e32 v101, v210, v101
	v_mul_f32_e32 v102, v210, v102
	v_mul_f32_e32 v103, v210, v103
	v_mul_f32_e32 v96, v210, v96
	v_mul_f32_e32 v97, v210, v97
	v_mul_f32_e32 v98, v210, v98
	v_mul_f32_e32 v99, v210, v99
	v_cvt_pk_bf16_f32 v244, v100, v101
	v_cvt_pk_bf16_f32 v245, v102, v103
	v_cvt_pk_bf16_f32 v246, v96, v97
	v_cvt_pk_bf16_f32 v247, v98, v99
	global_store_dwordx4 v150, v[244:247], s[42:43] offset:256
	v_mov_b32_e32 v174, 1.0
	v_mov_b32_e32 v175, 1.0
	v_mov_b32_e32 v176, 1.0
	v_mov_b32_e32 v177, 1.0
	v_mov_b32_e32 v178, 1.0
	v_mov_b32_e32 v179, 1.0
	v_mov_b32_e32 v180, 1.0
	v_mov_b32_e32 v181, 1.0
	v_mov_b32_e32 v182, 0
	v_mov_b32_e32 v183, 0
	v_mov_b32_e32 v184, 0
	v_mov_b32_e32 v185, 0
	v_mov_b32_e32 v186, 0
	v_mov_b32_e32 v187, 0
	v_mov_b32_e32 v188, 0
	v_mov_b32_e32 v189, 0
	v_add_u32_e32 v151, 0x2000, v211
	s_and_saveexec_b64 s[40:41], s[38:39]
	global_load_dwordx4 v[174:177], v151, s[20:21]
	global_load_dwordx4 v[178:181], v151, s[20:21] offset:16
	global_load_dwordx4 v[182:185], v151, s[20:21] offset:32
	global_load_dwordx4 v[186:189], v151, s[20:21] offset:48
	s_or_b64 exec, exec, s[40:41]
	s_waitcnt vmcnt(12)
	v_mul_f32_e32 v236, v209, v236
	v_mul_f32_e32 v237, v209, v237
	v_mul_f32_e32 v238, v209, v238
	v_mul_f32_e32 v239, v209, v239
	v_mul_f32_e32 v240, v209, v240
	v_mul_f32_e32 v241, v209, v241
	v_mul_f32_e32 v242, v209, v242
	v_mul_f32_e32 v243, v209, v243
	v_mul_f32_e32 v92, v92, v132
	v_mul_f32_e32 v93, v93, v132
	v_mul_f32_e32 v94, v94, v132
	v_mul_f32_e32 v95, v95, v132
	v_mul_f32_e32 v88, v88, v132
	v_mul_f32_e32 v89, v89, v132
	v_mul_f32_e32 v90, v90, v132
	v_mul_f32_e32 v91, v91, v132
	v_mul_f32_e32 v84, v84, v132
	v_mul_f32_e32 v85, v85, v132
	v_mul_f32_e32 v86, v86, v132
	v_mul_f32_e32 v87, v87, v132
	v_mul_f32_e32 v80, v80, v132
	v_mul_f32_e32 v81, v81, v132
	v_mul_f32_e32 v82, v82, v132
	v_mul_f32_e32 v83, v83, v132
	ds_bpermute_b32 v244, v208, v92
	ds_bpermute_b32 v245, v208, v93
	ds_bpermute_b32 v246, v208, v94
	ds_bpermute_b32 v247, v208, v95
	ds_bpermute_b32 v248, v208, v88
	ds_bpermute_b32 v249, v208, v89
	ds_bpermute_b32 v250, v208, v90
	ds_bpermute_b32 v251, v208, v91
	s_waitcnt lgkmcnt(0)
	v_mul_f32_e32 v244, v236, v244
	v_mul_f32_e32 v245, v237, v245
	v_mul_f32_e32 v246, v238, v246
	v_mul_f32_e32 v247, v239, v247
	v_mul_f32_e32 v248, v240, v248
	v_mul_f32_e32 v249, v241, v249
	v_mul_f32_e32 v250, v242, v250
	v_mul_f32_e32 v251, v243, v251
	v_fma_f32 v92, v92, v228, v244
	v_fma_f32 v93, v93, v229, v245
	v_fma_f32 v94, v94, v230, v246
	v_fma_f32 v95, v95, v231, v247
	v_fma_f32 v88, v88, v232, v248
	v_fma_f32 v89, v89, v233, v249
	v_fma_f32 v90, v90, v234, v250
	v_fma_f32 v91, v91, v235, v251
	v_mul_f32_e32 v92, v210, v92
	v_mul_f32_e32 v93, v210, v93
	v_mul_f32_e32 v94, v210, v94
	v_mul_f32_e32 v95, v210, v95
	v_mul_f32_e32 v88, v210, v88
	v_mul_f32_e32 v89, v210, v89
	v_mul_f32_e32 v90, v210, v90
	v_mul_f32_e32 v91, v210, v91
	v_cvt_pk_bf16_f32 v244, v92, v93
	v_cvt_pk_bf16_f32 v245, v94, v95
	v_cvt_pk_bf16_f32 v246, v88, v89
	v_cvt_pk_bf16_f32 v247, v90, v91
	v_add_u32_e32 v150, 0x10000, v112
	global_store_dwordx4 v150, v[244:247], s[42:43]
	s_nop 1
	ds_bpermute_b32 v244, v208, v84
	ds_bpermute_b32 v245, v208, v85
	ds_bpermute_b32 v246, v208, v86
	ds_bpermute_b32 v247, v208, v87
	ds_bpermute_b32 v248, v208, v80
	ds_bpermute_b32 v249, v208, v81
	ds_bpermute_b32 v250, v208, v82
	ds_bpermute_b32 v251, v208, v83
	s_waitcnt lgkmcnt(0)
	v_mul_f32_e32 v244, v236, v244
	v_mul_f32_e32 v245, v237, v245
	v_mul_f32_e32 v246, v238, v246
	v_mul_f32_e32 v247, v239, v247
	v_mul_f32_e32 v248, v240, v248
	v_mul_f32_e32 v249, v241, v249
	v_mul_f32_e32 v250, v242, v250
	v_mul_f32_e32 v251, v243, v251
	v_fma_f32 v84, v84, v228, v244
	v_fma_f32 v85, v85, v229, v245
	v_fma_f32 v86, v86, v230, v246
	v_fma_f32 v87, v87, v231, v247
	v_fma_f32 v80, v80, v232, v248
	v_fma_f32 v81, v81, v233, v249
	v_fma_f32 v82, v82, v234, v250
	v_fma_f32 v83, v83, v235, v251
	v_mul_f32_e32 v84, v210, v84
	v_mul_f32_e32 v85, v210, v85
	v_mul_f32_e32 v86, v210, v86
	v_mul_f32_e32 v87, v210, v87
	v_mul_f32_e32 v80, v210, v80
	v_mul_f32_e32 v81, v210, v81
	v_mul_f32_e32 v82, v210, v82
	v_mul_f32_e32 v83, v210, v83
	v_cvt_pk_bf16_f32 v244, v84, v85
	v_cvt_pk_bf16_f32 v245, v86, v87
	v_cvt_pk_bf16_f32 v246, v80, v81
	v_cvt_pk_bf16_f32 v247, v82, v83
	global_store_dwordx4 v150, v[244:247], s[42:43] offset:256
	v_mov_b32_e32 v228, 1.0
	v_mov_b32_e32 v229, 1.0
	v_mov_b32_e32 v230, 1.0
	v_mov_b32_e32 v231, 1.0
	v_mov_b32_e32 v232, 1.0
	v_mov_b32_e32 v233, 1.0
	v_mov_b32_e32 v234, 1.0
	v_mov_b32_e32 v235, 1.0
	v_mov_b32_e32 v236, 0
	v_mov_b32_e32 v237, 0
	v_mov_b32_e32 v238, 0
	v_mov_b32_e32 v239, 0
	v_mov_b32_e32 v240, 0
	v_mov_b32_e32 v241, 0
	v_mov_b32_e32 v242, 0
	v_mov_b32_e32 v243, 0
	v_add_u32_e32 v151, 0x2400, v211
	s_and_saveexec_b64 s[40:41], s[38:39]
	global_load_dwordx4 v[228:231], v151, s[20:21]
	global_load_dwordx4 v[232:235], v151, s[20:21] offset:16
	global_load_dwordx4 v[236:239], v151, s[20:21] offset:32
	global_load_dwordx4 v[240:243], v151, s[20:21] offset:48
	s_or_b64 exec, exec, s[40:41]
	s_waitcnt vmcnt(12)
	v_mul_f32_e32 v160, v209, v160
	v_mul_f32_e32 v161, v209, v161
	v_mul_f32_e32 v162, v209, v162
	v_mul_f32_e32 v163, v209, v163
	v_mul_f32_e32 v164, v209, v164
	v_mul_f32_e32 v165, v209, v165
	v_mul_f32_e32 v166, v209, v166
	v_mul_f32_e32 v167, v209, v167
	v_mul_f32_e32 v76, v76, v133
	v_mul_f32_e32 v77, v77, v133
	v_mul_f32_e32 v78, v78, v133
	v_mul_f32_e32 v79, v79, v133
	v_mul_f32_e32 v72, v72, v133
	v_mul_f32_e32 v73, v73, v133
	v_mul_f32_e32 v74, v74, v133
	v_mul_f32_e32 v75, v75, v133
	v_mul_f32_e32 v68, v68, v133
	v_mul_f32_e32 v69, v69, v133
	v_mul_f32_e32 v70, v70, v133
	v_mul_f32_e32 v71, v71, v133
	v_mul_f32_e32 v64, v64, v133
	v_mul_f32_e32 v65, v65, v133
	v_mul_f32_e32 v66, v66, v133
	v_mul_f32_e32 v67, v67, v133
	ds_bpermute_b32 v244, v208, v76
	ds_bpermute_b32 v245, v208, v77
	ds_bpermute_b32 v246, v208, v78
	ds_bpermute_b32 v247, v208, v79
	ds_bpermute_b32 v248, v208, v72
	ds_bpermute_b32 v249, v208, v73
	ds_bpermute_b32 v250, v208, v74
	ds_bpermute_b32 v251, v208, v75
	s_waitcnt lgkmcnt(0)
	v_mul_f32_e32 v244, v160, v244
	v_mul_f32_e32 v245, v161, v245
	v_mul_f32_e32 v246, v162, v246
	v_mul_f32_e32 v247, v163, v247
	v_mul_f32_e32 v248, v164, v248
	v_mul_f32_e32 v249, v165, v249
	v_mul_f32_e32 v250, v166, v250
	v_mul_f32_e32 v251, v167, v251
	v_fma_f32 v76, v76, v152, v244
	v_fma_f32 v77, v77, v153, v245
	v_fma_f32 v78, v78, v154, v246
	v_fma_f32 v79, v79, v155, v247
	v_fma_f32 v72, v72, v156, v248
	v_fma_f32 v73, v73, v157, v249
	v_fma_f32 v74, v74, v158, v250
	v_fma_f32 v75, v75, v159, v251
	v_mul_f32_e32 v76, v210, v76
	v_mul_f32_e32 v77, v210, v77
	v_mul_f32_e32 v78, v210, v78
	v_mul_f32_e32 v79, v210, v79
	v_mul_f32_e32 v72, v210, v72
	v_mul_f32_e32 v73, v210, v73
	v_mul_f32_e32 v74, v210, v74
	v_mul_f32_e32 v75, v210, v75
	v_cvt_pk_bf16_f32 v244, v76, v77
	v_cvt_pk_bf16_f32 v245, v78, v79
	v_cvt_pk_bf16_f32 v246, v72, v73
	v_cvt_pk_bf16_f32 v247, v74, v75
	v_add_u32_e32 v150, 0x18000, v112
	global_store_dwordx4 v150, v[244:247], s[42:43]
	s_nop 1
	ds_bpermute_b32 v244, v208, v68
	ds_bpermute_b32 v245, v208, v69
	ds_bpermute_b32 v246, v208, v70
	ds_bpermute_b32 v247, v208, v71
	ds_bpermute_b32 v248, v208, v64
	ds_bpermute_b32 v249, v208, v65
	ds_bpermute_b32 v250, v208, v66
	ds_bpermute_b32 v251, v208, v67
	s_waitcnt lgkmcnt(0)
	v_mul_f32_e32 v244, v160, v244
	v_mul_f32_e32 v245, v161, v245
	v_mul_f32_e32 v246, v162, v246
	v_mul_f32_e32 v247, v163, v247
	v_mul_f32_e32 v248, v164, v248
	v_mul_f32_e32 v249, v165, v249
	v_mul_f32_e32 v250, v166, v250
	v_mul_f32_e32 v251, v167, v251
	v_fma_f32 v68, v68, v152, v244
	v_fma_f32 v69, v69, v153, v245
	v_fma_f32 v70, v70, v154, v246
	v_fma_f32 v71, v71, v155, v247
	v_fma_f32 v64, v64, v156, v248
	v_fma_f32 v65, v65, v157, v249
	v_fma_f32 v66, v66, v158, v250
	v_fma_f32 v67, v67, v159, v251
	v_mul_f32_e32 v68, v210, v68
	v_mul_f32_e32 v69, v210, v69
	v_mul_f32_e32 v70, v210, v70
	v_mul_f32_e32 v71, v210, v71
	v_mul_f32_e32 v64, v210, v64
	v_mul_f32_e32 v65, v210, v65
	v_mul_f32_e32 v66, v210, v66
	v_mul_f32_e32 v67, v210, v67
	v_cvt_pk_bf16_f32 v244, v68, v69
	v_cvt_pk_bf16_f32 v245, v70, v71
	v_cvt_pk_bf16_f32 v246, v64, v65
	v_cvt_pk_bf16_f32 v247, v66, v67
	global_store_dwordx4 v150, v[244:247], s[42:43] offset:256
	v_mov_b32_e32 v152, 1.0
	v_mov_b32_e32 v153, 1.0
	v_mov_b32_e32 v154, 1.0
	v_mov_b32_e32 v155, 1.0
	v_mov_b32_e32 v156, 1.0
	v_mov_b32_e32 v157, 1.0
	v_mov_b32_e32 v158, 1.0
	v_mov_b32_e32 v159, 1.0
	v_mov_b32_e32 v160, 0
	v_mov_b32_e32 v161, 0
	v_mov_b32_e32 v162, 0
	v_mov_b32_e32 v163, 0
	v_mov_b32_e32 v164, 0
	v_mov_b32_e32 v165, 0
	v_mov_b32_e32 v166, 0
	v_mov_b32_e32 v167, 0
	v_add_u32_e32 v151, 0x2800, v211
	s_and_saveexec_b64 s[40:41], s[38:39]
	global_load_dwordx4 v[152:155], v151, s[20:21]
	global_load_dwordx4 v[156:159], v151, s[20:21] offset:16
	global_load_dwordx4 v[160:163], v151, s[20:21] offset:32
	global_load_dwordx4 v[164:167], v151, s[20:21] offset:48
	s_or_b64 exec, exec, s[40:41]
	s_waitcnt vmcnt(12)
	v_mul_f32_e32 v182, v209, v182
	v_mul_f32_e32 v183, v209, v183
	v_mul_f32_e32 v184, v209, v184
	v_mul_f32_e32 v185, v209, v185
	v_mul_f32_e32 v186, v209, v186
	v_mul_f32_e32 v187, v209, v187
	v_mul_f32_e32 v188, v209, v188
	v_mul_f32_e32 v189, v209, v189
	v_mul_f32_e32 v60, v60, v134
	v_mul_f32_e32 v61, v61, v134
	v_mul_f32_e32 v62, v62, v134
	v_mul_f32_e32 v63, v63, v134
	v_mul_f32_e32 v56, v56, v134
	v_mul_f32_e32 v57, v57, v134
	v_mul_f32_e32 v58, v58, v134
	v_mul_f32_e32 v59, v59, v134
	v_mul_f32_e32 v52, v52, v134
	v_mul_f32_e32 v53, v53, v134
	v_mul_f32_e32 v54, v54, v134
	v_mul_f32_e32 v55, v55, v134
	v_mul_f32_e32 v48, v48, v134
	v_mul_f32_e32 v49, v49, v134
	v_mul_f32_e32 v50, v50, v134
	v_mul_f32_e32 v51, v51, v134
	ds_bpermute_b32 v244, v208, v60
	ds_bpermute_b32 v245, v208, v61
	ds_bpermute_b32 v246, v208, v62
	ds_bpermute_b32 v247, v208, v63
	ds_bpermute_b32 v248, v208, v56
	ds_bpermute_b32 v249, v208, v57
	ds_bpermute_b32 v250, v208, v58
	ds_bpermute_b32 v251, v208, v59
	s_waitcnt lgkmcnt(0)
	v_mul_f32_e32 v244, v182, v244
	v_mul_f32_e32 v245, v183, v245
	v_mul_f32_e32 v246, v184, v246
	v_mul_f32_e32 v247, v185, v247
	v_mul_f32_e32 v248, v186, v248
	v_mul_f32_e32 v249, v187, v249
	v_mul_f32_e32 v250, v188, v250
	v_mul_f32_e32 v251, v189, v251
	v_fma_f32 v60, v60, v174, v244
	v_fma_f32 v61, v61, v175, v245
	v_fma_f32 v62, v62, v176, v246
	v_fma_f32 v63, v63, v177, v247
	v_fma_f32 v56, v56, v178, v248
	v_fma_f32 v57, v57, v179, v249
	v_fma_f32 v58, v58, v180, v250
	v_fma_f32 v59, v59, v181, v251
	v_mul_f32_e32 v60, v210, v60
	v_mul_f32_e32 v61, v210, v61
	v_mul_f32_e32 v62, v210, v62
	v_mul_f32_e32 v63, v210, v63
	v_mul_f32_e32 v56, v210, v56
	v_mul_f32_e32 v57, v210, v57
	v_mul_f32_e32 v58, v210, v58
	v_mul_f32_e32 v59, v210, v59
	v_cvt_pk_bf16_f32 v244, v60, v61
	v_cvt_pk_bf16_f32 v245, v62, v63
	v_cvt_pk_bf16_f32 v246, v56, v57
	v_cvt_pk_bf16_f32 v247, v58, v59
	v_add_u32_e32 v150, 0x40000, v112
	global_store_dwordx4 v150, v[244:247], s[42:43]
	s_nop 1
	ds_bpermute_b32 v244, v208, v52
	ds_bpermute_b32 v245, v208, v53
	ds_bpermute_b32 v246, v208, v54
	ds_bpermute_b32 v247, v208, v55
	ds_bpermute_b32 v248, v208, v48
	ds_bpermute_b32 v249, v208, v49
	ds_bpermute_b32 v250, v208, v50
	ds_bpermute_b32 v251, v208, v51
	s_waitcnt lgkmcnt(0)
	v_mul_f32_e32 v244, v182, v244
	v_mul_f32_e32 v245, v183, v245
	v_mul_f32_e32 v246, v184, v246
	v_mul_f32_e32 v247, v185, v247
	v_mul_f32_e32 v248, v186, v248
	v_mul_f32_e32 v249, v187, v249
	v_mul_f32_e32 v250, v188, v250
	v_mul_f32_e32 v251, v189, v251
	v_fma_f32 v52, v52, v174, v244
	v_fma_f32 v53, v53, v175, v245
	v_fma_f32 v54, v54, v176, v246
	v_fma_f32 v55, v55, v177, v247
	v_fma_f32 v48, v48, v178, v248
	v_fma_f32 v49, v49, v179, v249
	v_fma_f32 v50, v50, v180, v250
	v_fma_f32 v51, v51, v181, v251
	v_mul_f32_e32 v52, v210, v52
	v_mul_f32_e32 v53, v210, v53
	v_mul_f32_e32 v54, v210, v54
	v_mul_f32_e32 v55, v210, v55
	v_mul_f32_e32 v48, v210, v48
	v_mul_f32_e32 v49, v210, v49
	v_mul_f32_e32 v50, v210, v50
	v_mul_f32_e32 v51, v210, v51
	v_cvt_pk_bf16_f32 v244, v52, v53
	v_cvt_pk_bf16_f32 v245, v54, v55
	v_cvt_pk_bf16_f32 v246, v48, v49
	v_cvt_pk_bf16_f32 v247, v50, v51
	global_store_dwordx4 v150, v[244:247], s[42:43] offset:256
	v_mov_b32_e32 v174, 1.0
	v_mov_b32_e32 v175, 1.0
	v_mov_b32_e32 v176, 1.0
	v_mov_b32_e32 v177, 1.0
	v_mov_b32_e32 v178, 1.0
	v_mov_b32_e32 v179, 1.0
	v_mov_b32_e32 v180, 1.0
	v_mov_b32_e32 v181, 1.0
	v_mov_b32_e32 v182, 0
	v_mov_b32_e32 v183, 0
	v_mov_b32_e32 v184, 0
	v_mov_b32_e32 v185, 0
	v_mov_b32_e32 v186, 0
	v_mov_b32_e32 v187, 0
	v_mov_b32_e32 v188, 0
	v_mov_b32_e32 v189, 0
	v_add_u32_e32 v151, 0x2c00, v211
	s_and_saveexec_b64 s[40:41], s[38:39]
	global_load_dwordx4 v[174:177], v151, s[20:21]
	global_load_dwordx4 v[178:181], v151, s[20:21] offset:16
	global_load_dwordx4 v[182:185], v151, s[20:21] offset:32
	global_load_dwordx4 v[186:189], v151, s[20:21] offset:48
	s_or_b64 exec, exec, s[40:41]
	s_waitcnt vmcnt(12)
	v_mul_f32_e32 v236, v209, v236
	v_mul_f32_e32 v237, v209, v237
	v_mul_f32_e32 v238, v209, v238
	v_mul_f32_e32 v239, v209, v239
	v_mul_f32_e32 v240, v209, v240
	v_mul_f32_e32 v241, v209, v241
	v_mul_f32_e32 v242, v209, v242
	v_mul_f32_e32 v243, v209, v243
	v_mul_f32_e32 v44, v44, v135
	v_mul_f32_e32 v45, v45, v135
	v_mul_f32_e32 v46, v46, v135
	v_mul_f32_e32 v47, v47, v135
	v_mul_f32_e32 v40, v40, v135
	v_mul_f32_e32 v41, v41, v135
	v_mul_f32_e32 v42, v42, v135
	v_mul_f32_e32 v43, v43, v135
	v_mul_f32_e32 v36, v36, v135
	v_mul_f32_e32 v37, v37, v135
	v_mul_f32_e32 v38, v38, v135
	v_mul_f32_e32 v39, v39, v135
	v_mul_f32_e32 v32, v32, v135
	v_mul_f32_e32 v33, v33, v135
	v_mul_f32_e32 v34, v34, v135
	v_mul_f32_e32 v35, v35, v135
	ds_bpermute_b32 v244, v208, v44
	ds_bpermute_b32 v245, v208, v45
	ds_bpermute_b32 v246, v208, v46
	ds_bpermute_b32 v247, v208, v47
	ds_bpermute_b32 v248, v208, v40
	ds_bpermute_b32 v249, v208, v41
	ds_bpermute_b32 v250, v208, v42
	ds_bpermute_b32 v251, v208, v43
	s_waitcnt lgkmcnt(0)
	v_mul_f32_e32 v244, v236, v244
	v_mul_f32_e32 v245, v237, v245
	v_mul_f32_e32 v246, v238, v246
	v_mul_f32_e32 v247, v239, v247
	v_mul_f32_e32 v248, v240, v248
	v_mul_f32_e32 v249, v241, v249
	v_mul_f32_e32 v250, v242, v250
	v_mul_f32_e32 v251, v243, v251
	v_fma_f32 v44, v44, v228, v244
	v_fma_f32 v45, v45, v229, v245
	v_fma_f32 v46, v46, v230, v246
	v_fma_f32 v47, v47, v231, v247
	v_fma_f32 v40, v40, v232, v248
	v_fma_f32 v41, v41, v233, v249
	v_fma_f32 v42, v42, v234, v250
	v_fma_f32 v43, v43, v235, v251
	v_mul_f32_e32 v44, v210, v44
	v_mul_f32_e32 v45, v210, v45
	v_mul_f32_e32 v46, v210, v46
	v_mul_f32_e32 v47, v210, v47
	v_mul_f32_e32 v40, v210, v40
	v_mul_f32_e32 v41, v210, v41
	v_mul_f32_e32 v42, v210, v42
	v_mul_f32_e32 v43, v210, v43
	v_cvt_pk_bf16_f32 v244, v44, v45
	v_cvt_pk_bf16_f32 v245, v46, v47
	v_cvt_pk_bf16_f32 v246, v40, v41
	v_cvt_pk_bf16_f32 v247, v42, v43
	v_add_u32_e32 v150, 0x48000, v112
	global_store_dwordx4 v150, v[244:247], s[42:43]
	s_nop 1
	ds_bpermute_b32 v244, v208, v36
	ds_bpermute_b32 v245, v208, v37
	ds_bpermute_b32 v246, v208, v38
	ds_bpermute_b32 v247, v208, v39
	ds_bpermute_b32 v248, v208, v32
	ds_bpermute_b32 v249, v208, v33
	ds_bpermute_b32 v250, v208, v34
	ds_bpermute_b32 v251, v208, v35
	s_waitcnt lgkmcnt(0)
	v_mul_f32_e32 v244, v236, v244
	v_mul_f32_e32 v245, v237, v245
	v_mul_f32_e32 v246, v238, v246
	v_mul_f32_e32 v247, v239, v247
	v_mul_f32_e32 v248, v240, v248
	v_mul_f32_e32 v249, v241, v249
	v_mul_f32_e32 v250, v242, v250
	v_mul_f32_e32 v251, v243, v251
	v_fma_f32 v36, v36, v228, v244
	v_fma_f32 v37, v37, v229, v245
	v_fma_f32 v38, v38, v230, v246
	v_fma_f32 v39, v39, v231, v247
	v_fma_f32 v32, v32, v232, v248
	v_fma_f32 v33, v33, v233, v249
	v_fma_f32 v34, v34, v234, v250
	v_fma_f32 v35, v35, v235, v251
	v_mul_f32_e32 v36, v210, v36
	v_mul_f32_e32 v37, v210, v37
	v_mul_f32_e32 v38, v210, v38
	v_mul_f32_e32 v39, v210, v39
	v_mul_f32_e32 v32, v210, v32
	v_mul_f32_e32 v33, v210, v33
	v_mul_f32_e32 v34, v210, v34
	v_mul_f32_e32 v35, v210, v35
	v_cvt_pk_bf16_f32 v244, v36, v37
	v_cvt_pk_bf16_f32 v245, v38, v39
	v_cvt_pk_bf16_f32 v246, v32, v33
	v_cvt_pk_bf16_f32 v247, v34, v35
	global_store_dwordx4 v150, v[244:247], s[42:43] offset:256
	s_waitcnt vmcnt(8)
	v_mul_f32_e32 v160, v209, v160
	v_mul_f32_e32 v161, v209, v161
	v_mul_f32_e32 v162, v209, v162
	v_mul_f32_e32 v163, v209, v163
	v_mul_f32_e32 v164, v209, v164
	v_mul_f32_e32 v165, v209, v165
	v_mul_f32_e32 v166, v209, v166
	v_mul_f32_e32 v167, v209, v167
	v_mul_f32_e32 v28, v28, v136
	v_mul_f32_e32 v29, v29, v136
	v_mul_f32_e32 v30, v30, v136
	v_mul_f32_e32 v31, v31, v136
	v_mul_f32_e32 v24, v24, v136
	v_mul_f32_e32 v25, v25, v136
	v_mul_f32_e32 v26, v26, v136
	v_mul_f32_e32 v27, v27, v136
	v_mul_f32_e32 v20, v20, v136
	v_mul_f32_e32 v21, v21, v136
	v_mul_f32_e32 v22, v22, v136
	v_mul_f32_e32 v23, v23, v136
	v_mul_f32_e32 v16, v16, v136
	v_mul_f32_e32 v17, v17, v136
	v_mul_f32_e32 v18, v18, v136
	v_mul_f32_e32 v19, v19, v136
	ds_bpermute_b32 v244, v208, v28
	ds_bpermute_b32 v245, v208, v29
	ds_bpermute_b32 v246, v208, v30
	ds_bpermute_b32 v247, v208, v31
	ds_bpermute_b32 v248, v208, v24
	ds_bpermute_b32 v249, v208, v25
	ds_bpermute_b32 v250, v208, v26
	ds_bpermute_b32 v251, v208, v27
	s_waitcnt lgkmcnt(0)
	v_mul_f32_e32 v244, v160, v244
	v_mul_f32_e32 v245, v161, v245
	v_mul_f32_e32 v246, v162, v246
	v_mul_f32_e32 v247, v163, v247
	v_mul_f32_e32 v248, v164, v248
	v_mul_f32_e32 v249, v165, v249
	v_mul_f32_e32 v250, v166, v250
	v_mul_f32_e32 v251, v167, v251
	v_fma_f32 v28, v28, v152, v244
	v_fma_f32 v29, v29, v153, v245
	v_fma_f32 v30, v30, v154, v246
	v_fma_f32 v31, v31, v155, v247
	v_fma_f32 v24, v24, v156, v248
	v_fma_f32 v25, v25, v157, v249
	v_fma_f32 v26, v26, v158, v250
	v_fma_f32 v27, v27, v159, v251
	v_mul_f32_e32 v28, v210, v28
	v_mul_f32_e32 v29, v210, v29
	v_mul_f32_e32 v30, v210, v30
	v_mul_f32_e32 v31, v210, v31
	v_mul_f32_e32 v24, v210, v24
	v_mul_f32_e32 v25, v210, v25
	v_mul_f32_e32 v26, v210, v26
	v_mul_f32_e32 v27, v210, v27
	v_cvt_pk_bf16_f32 v244, v28, v29
	v_cvt_pk_bf16_f32 v245, v30, v31
	v_cvt_pk_bf16_f32 v246, v24, v25
	v_cvt_pk_bf16_f32 v247, v26, v27
	v_add_u32_e32 v150, 0x50000, v112
	global_store_dwordx4 v150, v[244:247], s[42:43]
	s_nop 1
	ds_bpermute_b32 v244, v208, v20
	ds_bpermute_b32 v245, v208, v21
	ds_bpermute_b32 v246, v208, v22
	ds_bpermute_b32 v247, v208, v23
	ds_bpermute_b32 v248, v208, v16
	ds_bpermute_b32 v249, v208, v17
	ds_bpermute_b32 v250, v208, v18
	ds_bpermute_b32 v251, v208, v19
	s_waitcnt lgkmcnt(0)
	v_mul_f32_e32 v244, v160, v244
	v_mul_f32_e32 v245, v161, v245
	v_mul_f32_e32 v246, v162, v246
	v_mul_f32_e32 v247, v163, v247
	v_mul_f32_e32 v248, v164, v248
	v_mul_f32_e32 v249, v165, v249
	v_mul_f32_e32 v250, v166, v250
	v_mul_f32_e32 v251, v167, v251
	v_fma_f32 v20, v20, v152, v244
	v_fma_f32 v21, v21, v153, v245
	v_fma_f32 v22, v22, v154, v246
	v_fma_f32 v23, v23, v155, v247
	v_fma_f32 v16, v16, v156, v248
	v_fma_f32 v17, v17, v157, v249
	v_fma_f32 v18, v18, v158, v250
	v_fma_f32 v19, v19, v159, v251
	v_mul_f32_e32 v20, v210, v20
	v_mul_f32_e32 v21, v210, v21
	v_mul_f32_e32 v22, v210, v22
	v_mul_f32_e32 v23, v210, v23
	v_mul_f32_e32 v16, v210, v16
	v_mul_f32_e32 v17, v210, v17
	v_mul_f32_e32 v18, v210, v18
	v_mul_f32_e32 v19, v210, v19
	v_cvt_pk_bf16_f32 v244, v20, v21
	v_cvt_pk_bf16_f32 v245, v22, v23
	v_cvt_pk_bf16_f32 v246, v16, v17
	v_cvt_pk_bf16_f32 v247, v18, v19
	global_store_dwordx4 v150, v[244:247], s[42:43] offset:256
	s_waitcnt vmcnt(4)
	v_mul_f32_e32 v182, v209, v182
	v_mul_f32_e32 v183, v209, v183
	v_mul_f32_e32 v184, v209, v184
	v_mul_f32_e32 v185, v209, v185
	v_mul_f32_e32 v186, v209, v186
	v_mul_f32_e32 v187, v209, v187
	v_mul_f32_e32 v188, v209, v188
	v_mul_f32_e32 v189, v209, v189
	v_mul_f32_e32 v12, v12, v137
	v_mul_f32_e32 v13, v13, v137
	v_mul_f32_e32 v14, v14, v137
	v_mul_f32_e32 v15, v15, v137
	v_mul_f32_e32 v8, v8, v137
	v_mul_f32_e32 v9, v9, v137
	v_mul_f32_e32 v10, v10, v137
	v_mul_f32_e32 v11, v11, v137
	v_mul_f32_e32 v4, v4, v137
	v_mul_f32_e32 v5, v5, v137
	v_mul_f32_e32 v6, v6, v137
	v_mul_f32_e32 v7, v7, v137
	v_mul_f32_e32 v0, v0, v137
	v_mul_f32_e32 v1, v1, v137
	v_mul_f32_e32 v2, v2, v137
	v_mul_f32_e32 v3, v3, v137
	ds_bpermute_b32 v244, v208, v12
	ds_bpermute_b32 v245, v208, v13
	ds_bpermute_b32 v246, v208, v14
	ds_bpermute_b32 v247, v208, v15
	ds_bpermute_b32 v248, v208, v8
	ds_bpermute_b32 v249, v208, v9
	ds_bpermute_b32 v250, v208, v10
	ds_bpermute_b32 v251, v208, v11
	s_waitcnt lgkmcnt(0)
	v_mul_f32_e32 v244, v182, v244
	v_mul_f32_e32 v245, v183, v245
	v_mul_f32_e32 v246, v184, v246
	v_mul_f32_e32 v247, v185, v247
	v_mul_f32_e32 v248, v186, v248
	v_mul_f32_e32 v249, v187, v249
	v_mul_f32_e32 v250, v188, v250
	v_mul_f32_e32 v251, v189, v251
	v_fma_f32 v12, v12, v174, v244
	v_fma_f32 v13, v13, v175, v245
	v_fma_f32 v14, v14, v176, v246
	v_fma_f32 v15, v15, v177, v247
	v_fma_f32 v8, v8, v178, v248
	v_fma_f32 v9, v9, v179, v249
	v_fma_f32 v10, v10, v180, v250
	v_fma_f32 v11, v11, v181, v251
	v_mul_f32_e32 v12, v210, v12
	v_mul_f32_e32 v13, v210, v13
	v_mul_f32_e32 v14, v210, v14
	v_mul_f32_e32 v15, v210, v15
	v_mul_f32_e32 v8, v210, v8
	v_mul_f32_e32 v9, v210, v9
	v_mul_f32_e32 v10, v210, v10
	v_mul_f32_e32 v11, v210, v11
	v_cvt_pk_bf16_f32 v244, v12, v13
	v_cvt_pk_bf16_f32 v245, v14, v15
	v_cvt_pk_bf16_f32 v246, v8, v9
	v_cvt_pk_bf16_f32 v247, v10, v11
	v_add_u32_e32 v150, 0x58000, v112
	global_store_dwordx4 v150, v[244:247], s[42:43]
	s_nop 1
	ds_bpermute_b32 v244, v208, v4
	ds_bpermute_b32 v245, v208, v5
	ds_bpermute_b32 v246, v208, v6
	ds_bpermute_b32 v247, v208, v7
	ds_bpermute_b32 v248, v208, v0
	ds_bpermute_b32 v249, v208, v1
	ds_bpermute_b32 v250, v208, v2
	ds_bpermute_b32 v251, v208, v3
	s_waitcnt lgkmcnt(0)
	v_mul_f32_e32 v244, v182, v244
	v_mul_f32_e32 v245, v183, v245
	v_mul_f32_e32 v246, v184, v246
	v_mul_f32_e32 v247, v185, v247
	v_mul_f32_e32 v248, v186, v248
	v_mul_f32_e32 v249, v187, v249
	v_mul_f32_e32 v250, v188, v250
	v_mul_f32_e32 v251, v189, v251
	v_fma_f32 v4, v4, v174, v244
	v_fma_f32 v5, v5, v175, v245
	v_fma_f32 v6, v6, v176, v246
	v_fma_f32 v7, v7, v177, v247
	v_fma_f32 v0, v0, v178, v248
	v_fma_f32 v1, v1, v179, v249
	v_fma_f32 v2, v2, v180, v250
	v_fma_f32 v3, v3, v181, v251
	v_mul_f32_e32 v4, v210, v4
	v_mul_f32_e32 v5, v210, v5
	v_mul_f32_e32 v6, v210, v6
	v_mul_f32_e32 v7, v210, v7
	v_mul_f32_e32 v0, v210, v0
	v_mul_f32_e32 v1, v210, v1
	v_mul_f32_e32 v2, v210, v2
	v_mul_f32_e32 v3, v210, v3
	v_cvt_pk_bf16_f32 v244, v4, v5
	v_cvt_pk_bf16_f32 v245, v6, v7
	v_cvt_pk_bf16_f32 v246, v0, v1
	v_cvt_pk_bf16_f32 v247, v2, v3
	global_store_dwordx4 v150, v[244:247], s[42:43] offset:256
	s_branch .Lqkv_done
.Lqkv_plain:
	s_waitcnt lgkmcnt(0)
	v_mul_f32_e32 v126, v126, v130
	v_mul_f32_e32 v127, v127, v130
	v_mul_f32_e32 v128, v128, v130
	v_mul_f32_e32 v129, v129, v130
	v_mul_f32_e32 v122, v122, v130
	v_mul_f32_e32 v123, v123, v130
	v_mul_f32_e32 v124, v124, v130
	v_mul_f32_e32 v125, v125, v130
	v_mul_f32_e32 v118, v118, v130
	v_mul_f32_e32 v119, v119, v130
	v_mul_f32_e32 v120, v120, v130
	v_mul_f32_e32 v121, v121, v130
	v_mul_f32_e32 v114, v114, v130
	v_mul_f32_e32 v115, v115, v130
	v_mul_f32_e32 v116, v116, v130
	v_mul_f32_e32 v117, v117, v130
	v_mul_f32_e32 v126, v210, v126
	v_mul_f32_e32 v127, v210, v127
	v_mul_f32_e32 v128, v210, v128
	v_mul_f32_e32 v129, v210, v129
	v_mul_f32_e32 v122, v210, v122
	v_mul_f32_e32 v123, v210, v123
	v_mul_f32_e32 v124, v210, v124
	v_mul_f32_e32 v125, v210, v125
	v_mul_f32_e32 v118, v210, v118
	v_mul_f32_e32 v119, v210, v119
	v_mul_f32_e32 v120, v210, v120
	v_mul_f32_e32 v121, v210, v121
	v_mul_f32_e32 v114, v210, v114
	v_mul_f32_e32 v115, v210, v115
	v_mul_f32_e32 v116, v210, v116
	v_mul_f32_e32 v117, v210, v117
	v_cvt_pk_bf16_f32 v244, v126, v127
	v_cvt_pk_bf16_f32 v245, v128, v129
	v_cvt_pk_bf16_f32 v246, v122, v123
	v_cvt_pk_bf16_f32 v247, v124, v125
	v_cvt_pk_bf16_f32 v248, v118, v119
	v_cvt_pk_bf16_f32 v249, v120, v121
	v_cvt_pk_bf16_f32 v250, v114, v115
	v_cvt_pk_bf16_f32 v251, v116, v117
	global_store_dwordx4 v112, v[244:247], s[42:43]
	global_store_dwordx4 v112, v[248:251], s[42:43] offset:256
	v_mul_f32_e32 v108, v108, v131
	v_mul_f32_e32 v109, v109, v131
	v_mul_f32_e32 v110, v110, v131
	v_mul_f32_e32 v111, v111, v131
	v_mul_f32_e32 v104, v104, v131
	v_mul_f32_e32 v105, v105, v131
	v_mul_f32_e32 v106, v106, v131
	v_mul_f32_e32 v107, v107, v131
	v_mul_f32_e32 v100, v100, v131
	v_mul_f32_e32 v101, v101, v131
	v_mul_f32_e32 v102, v102, v131
	v_mul_f32_e32 v103, v103, v131
	v_mul_f32_e32 v96, v96, v131
	v_mul_f32_e32 v97, v97, v131
	v_mul_f32_e32 v98, v98, v131
	v_mul_f32_e32 v99, v99, v131
	v_mul_f32_e32 v108, v210, v108
	v_mul_f32_e32 v109, v210, v109
	v_mul_f32_e32 v110, v210, v110
	v_mul_f32_e32 v111, v210, v111
	v_mul_f32_e32 v104, v210, v104
	v_mul_f32_e32 v105, v210, v105
	v_mul_f32_e32 v106, v210, v106
	v_mul_f32_e32 v107, v210, v107
	v_mul_f32_e32 v100, v210, v100
	v_mul_f32_e32 v101, v210, v101
	v_mul_f32_e32 v102, v210, v102
	v_mul_f32_e32 v103, v210, v103
	v_mul_f32_e32 v96, v210, v96
	v_mul_f32_e32 v97, v210, v97
	v_mul_f32_e32 v98, v210, v98
	v_mul_f32_e32 v99, v210, v99
	v_cvt_pk_bf16_f32 v228, v108, v109
	v_cvt_pk_bf16_f32 v229, v110, v111
	v_cvt_pk_bf16_f32 v230, v104, v105
	v_cvt_pk_bf16_f32 v231, v106, v107
	v_cvt_pk_bf16_f32 v232, v100, v101
	v_cvt_pk_bf16_f32 v233, v102, v103
	v_cvt_pk_bf16_f32 v234, v96, v97
	v_cvt_pk_bf16_f32 v235, v98, v99
	v_add_u32_e32 v150, 0x8000, v112
	global_store_dwordx4 v150, v[228:231], s[42:43]
	global_store_dwordx4 v150, v[232:235], s[42:43] offset:256
	v_mul_f32_e32 v92, v92, v132
	v_mul_f32_e32 v93, v93, v132
	v_mul_f32_e32 v94, v94, v132
	v_mul_f32_e32 v95, v95, v132
	v_mul_f32_e32 v88, v88, v132
	v_mul_f32_e32 v89, v89, v132
	v_mul_f32_e32 v90, v90, v132
	v_mul_f32_e32 v91, v91, v132
	v_mul_f32_e32 v84, v84, v132
	v_mul_f32_e32 v85, v85, v132
	v_mul_f32_e32 v86, v86, v132
	v_mul_f32_e32 v87, v87, v132
	v_mul_f32_e32 v80, v80, v132
	v_mul_f32_e32 v81, v81, v132
	v_mul_f32_e32 v82, v82, v132
	v_mul_f32_e32 v83, v83, v132
	v_mul_f32_e32 v92, v210, v92
	v_mul_f32_e32 v93, v210, v93
	v_mul_f32_e32 v94, v210, v94
	v_mul_f32_e32 v95, v210, v95
	v_mul_f32_e32 v88, v210, v88
	v_mul_f32_e32 v89, v210, v89
	v_mul_f32_e32 v90, v210, v90
	v_mul_f32_e32 v91, v210, v91
	v_mul_f32_e32 v84, v210, v84
	v_mul_f32_e32 v85, v210, v85
	v_mul_f32_e32 v86, v210, v86
	v_mul_f32_e32 v87, v210, v87
	v_mul_f32_e32 v80, v210, v80
	v_mul_f32_e32 v81, v210, v81
	v_mul_f32_e32 v82, v210, v82
	v_mul_f32_e32 v83, v210, v83
	v_cvt_pk_bf16_f32 v244, v92, v93
	v_cvt_pk_bf16_f32 v245, v94, v95
	v_cvt_pk_bf16_f32 v246, v88, v89
	v_cvt_pk_bf16_f32 v247, v90, v91
	v_cvt_pk_bf16_f32 v248, v84, v85
	v_cvt_pk_bf16_f32 v249, v86, v87
	v_cvt_pk_bf16_f32 v250, v80, v81
	v_cvt_pk_bf16_f32 v251, v82, v83
	v_add_u32_e32 v151, 0x10000, v112
	global_store_dwordx4 v151, v[244:247], s[42:43]
	global_store_dwordx4 v151, v[248:251], s[42:43] offset:256
	v_mul_f32_e32 v76, v76, v133
	v_mul_f32_e32 v77, v77, v133
	v_mul_f32_e32 v78, v78, v133
	v_mul_f32_e32 v79, v79, v133
	v_mul_f32_e32 v72, v72, v133
	v_mul_f32_e32 v73, v73, v133
	v_mul_f32_e32 v74, v74, v133
	v_mul_f32_e32 v75, v75, v133
	v_mul_f32_e32 v68, v68, v133
	v_mul_f32_e32 v69, v69, v133
	v_mul_f32_e32 v70, v70, v133
	v_mul_f32_e32 v71, v71, v133
	v_mul_f32_e32 v64, v64, v133
	v_mul_f32_e32 v65, v65, v133
	v_mul_f32_e32 v66, v66, v133
	v_mul_f32_e32 v67, v67, v133
	v_mul_f32_e32 v76, v210, v76
	v_mul_f32_e32 v77, v210, v77
	v_mul_f32_e32 v78, v210, v78
	v_mul_f32_e32 v79, v210, v79
	v_mul_f32_e32 v72, v210, v72
	v_mul_f32_e32 v73, v210, v73
	v_mul_f32_e32 v74, v210, v74
	v_mul_f32_e32 v75, v210, v75
	v_mul_f32_e32 v68, v210, v68
	v_mul_f32_e32 v69, v210, v69
	v_mul_f32_e32 v70, v210, v70
	v_mul_f32_e32 v71, v210, v71
	v_mul_f32_e32 v64, v210, v64
	v_mul_f32_e32 v65, v210, v65
	v_mul_f32_e32 v66, v210, v66
	v_mul_f32_e32 v67, v210, v67
	v_cvt_pk_bf16_f32 v228, v76, v77
	v_cvt_pk_bf16_f32 v229, v78, v79
	v_cvt_pk_bf16_f32 v230, v72, v73
	v_cvt_pk_bf16_f32 v231, v74, v75
	v_cvt_pk_bf16_f32 v232, v68, v69
	v_cvt_pk_bf16_f32 v233, v70, v71
	v_cvt_pk_bf16_f32 v234, v64, v65
	v_cvt_pk_bf16_f32 v235, v66, v67
	v_add_u32_e32 v150, 0x18000, v112
	global_store_dwordx4 v150, v[228:231], s[42:43]
	global_store_dwordx4 v150, v[232:235], s[42:43] offset:256
	v_mul_f32_e32 v60, v60, v134
	v_mul_f32_e32 v61, v61, v134
	v_mul_f32_e32 v62, v62, v134
	v_mul_f32_e32 v63, v63, v134
	v_mul_f32_e32 v56, v56, v134
	v_mul_f32_e32 v57, v57, v134
	v_mul_f32_e32 v58, v58, v134
	v_mul_f32_e32 v59, v59, v134
	v_mul_f32_e32 v52, v52, v134
	v_mul_f32_e32 v53, v53, v134
	v_mul_f32_e32 v54, v54, v134
	v_mul_f32_e32 v55, v55, v134
	v_mul_f32_e32 v48, v48, v134
	v_mul_f32_e32 v49, v49, v134
	v_mul_f32_e32 v50, v50, v134
	v_mul_f32_e32 v51, v51, v134
	v_mul_f32_e32 v60, v210, v60
	v_mul_f32_e32 v61, v210, v61
	v_mul_f32_e32 v62, v210, v62
	v_mul_f32_e32 v63, v210, v63
	v_mul_f32_e32 v56, v210, v56
	v_mul_f32_e32 v57, v210, v57
	v_mul_f32_e32 v58, v210, v58
	v_mul_f32_e32 v59, v210, v59
	v_mul_f32_e32 v52, v210, v52
	v_mul_f32_e32 v53, v210, v53
	v_mul_f32_e32 v54, v210, v54
	v_mul_f32_e32 v55, v210, v55
	v_mul_f32_e32 v48, v210, v48
	v_mul_f32_e32 v49, v210, v49
	v_mul_f32_e32 v50, v210, v50
	v_mul_f32_e32 v51, v210, v51
	v_cvt_pk_bf16_f32 v244, v60, v61
	v_cvt_pk_bf16_f32 v245, v62, v63
	v_cvt_pk_bf16_f32 v246, v56, v57
	v_cvt_pk_bf16_f32 v247, v58, v59
	v_cvt_pk_bf16_f32 v248, v52, v53
	v_cvt_pk_bf16_f32 v249, v54, v55
	v_cvt_pk_bf16_f32 v250, v48, v49
	v_cvt_pk_bf16_f32 v251, v50, v51
	v_add_u32_e32 v151, 0x40000, v112
	global_store_dwordx4 v151, v[244:247], s[42:43]
	global_store_dwordx4 v151, v[248:251], s[42:43] offset:256
	v_mul_f32_e32 v44, v44, v135
	v_mul_f32_e32 v45, v45, v135
	v_mul_f32_e32 v46, v46, v135
	v_mul_f32_e32 v47, v47, v135
	v_mul_f32_e32 v40, v40, v135
	v_mul_f32_e32 v41, v41, v135
	v_mul_f32_e32 v42, v42, v135
	v_mul_f32_e32 v43, v43, v135
	v_mul_f32_e32 v36, v36, v135
	v_mul_f32_e32 v37, v37, v135
	v_mul_f32_e32 v38, v38, v135
	v_mul_f32_e32 v39, v39, v135
	v_mul_f32_e32 v32, v32, v135
	v_mul_f32_e32 v33, v33, v135
	v_mul_f32_e32 v34, v34, v135
	v_mul_f32_e32 v35, v35, v135
	v_mul_f32_e32 v44, v210, v44
	v_mul_f32_e32 v45, v210, v45
	v_mul_f32_e32 v46, v210, v46
	v_mul_f32_e32 v47, v210, v47
	v_mul_f32_e32 v40, v210, v40
	v_mul_f32_e32 v41, v210, v41
	v_mul_f32_e32 v42, v210, v42
	v_mul_f32_e32 v43, v210, v43
	v_mul_f32_e32 v36, v210, v36
	v_mul_f32_e32 v37, v210, v37
	v_mul_f32_e32 v38, v210, v38
	v_mul_f32_e32 v39, v210, v39
	v_mul_f32_e32 v32, v210, v32
	v_mul_f32_e32 v33, v210, v33
	v_mul_f32_e32 v34, v210, v34
	v_mul_f32_e32 v35, v210, v35
	v_cvt_pk_bf16_f32 v228, v44, v45
	v_cvt_pk_bf16_f32 v229, v46, v47
	v_cvt_pk_bf16_f32 v230, v40, v41
	v_cvt_pk_bf16_f32 v231, v42, v43
	v_cvt_pk_bf16_f32 v232, v36, v37
	v_cvt_pk_bf16_f32 v233, v38, v39
	v_cvt_pk_bf16_f32 v234, v32, v33
	v_cvt_pk_bf16_f32 v235, v34, v35
	v_add_u32_e32 v150, 0x48000, v112
	global_store_dwordx4 v150, v[228:231], s[42:43]
	global_store_dwordx4 v150, v[232:235], s[42:43] offset:256
	v_mul_f32_e32 v28, v28, v136
	v_mul_f32_e32 v29, v29, v136
	v_mul_f32_e32 v30, v30, v136
	v_mul_f32_e32 v31, v31, v136
	v_mul_f32_e32 v24, v24, v136
	v_mul_f32_e32 v25, v25, v136
	v_mul_f32_e32 v26, v26, v136
	v_mul_f32_e32 v27, v27, v136
	v_mul_f32_e32 v20, v20, v136
	v_mul_f32_e32 v21, v21, v136
	v_mul_f32_e32 v22, v22, v136
	v_mul_f32_e32 v23, v23, v136
	v_mul_f32_e32 v16, v16, v136
	v_mul_f32_e32 v17, v17, v136
	v_mul_f32_e32 v18, v18, v136
	v_mul_f32_e32 v19, v19, v136
	v_mul_f32_e32 v28, v210, v28
	v_mul_f32_e32 v29, v210, v29
	v_mul_f32_e32 v30, v210, v30
	v_mul_f32_e32 v31, v210, v31
	v_mul_f32_e32 v24, v210, v24
	v_mul_f32_e32 v25, v210, v25
	v_mul_f32_e32 v26, v210, v26
	v_mul_f32_e32 v27, v210, v27
	v_mul_f32_e32 v20, v210, v20
	v_mul_f32_e32 v21, v210, v21
	v_mul_f32_e32 v22, v210, v22
	v_mul_f32_e32 v23, v210, v23
	v_mul_f32_e32 v16, v210, v16
	v_mul_f32_e32 v17, v210, v17
	v_mul_f32_e32 v18, v210, v18
	v_mul_f32_e32 v19, v210, v19
	v_cvt_pk_bf16_f32 v244, v28, v29
	v_cvt_pk_bf16_f32 v245, v30, v31
	v_cvt_pk_bf16_f32 v246, v24, v25
	v_cvt_pk_bf16_f32 v247, v26, v27
	v_cvt_pk_bf16_f32 v248, v20, v21
	v_cvt_pk_bf16_f32 v249, v22, v23
	v_cvt_pk_bf16_f32 v250, v16, v17
	v_cvt_pk_bf16_f32 v251, v18, v19
	v_add_u32_e32 v151, 0x50000, v112
	global_store_dwordx4 v151, v[244:247], s[42:43]
	global_store_dwordx4 v151, v[248:251], s[42:43] offset:256
	v_mul_f32_e32 v12, v12, v137
	v_mul_f32_e32 v13, v13, v137
	v_mul_f32_e32 v14, v14, v137
	v_mul_f32_e32 v15, v15, v137
	v_mul_f32_e32 v8, v8, v137
	v_mul_f32_e32 v9, v9, v137
	v_mul_f32_e32 v10, v10, v137
	v_mul_f32_e32 v11, v11, v137
	v_mul_f32_e32 v4, v4, v137
	v_mul_f32_e32 v5, v5, v137
	v_mul_f32_e32 v6, v6, v137
	v_mul_f32_e32 v7, v7, v137
	v_mul_f32_e32 v0, v0, v137
	v_mul_f32_e32 v1, v1, v137
	v_mul_f32_e32 v2, v2, v137
	v_mul_f32_e32 v3, v3, v137
	v_mul_f32_e32 v12, v210, v12
	v_mul_f32_e32 v13, v210, v13
	v_mul_f32_e32 v14, v210, v14
	v_mul_f32_e32 v15, v210, v15
	v_mul_f32_e32 v8, v210, v8
	v_mul_f32_e32 v9, v210, v9
	v_mul_f32_e32 v10, v210, v10
	v_mul_f32_e32 v11, v210, v11
	v_mul_f32_e32 v4, v210, v4
	v_mul_f32_e32 v5, v210, v5
	v_mul_f32_e32 v6, v210, v6
	v_mul_f32_e32 v7, v210, v7
	v_mul_f32_e32 v0, v210, v0
	v_mul_f32_e32 v1, v210, v1
	v_mul_f32_e32 v2, v210, v2
	v_mul_f32_e32 v3, v210, v3
	v_cvt_pk_bf16_f32 v228, v12, v13
	v_cvt_pk_bf16_f32 v229, v14, v15
	v_cvt_pk_bf16_f32 v230, v8, v9
	v_cvt_pk_bf16_f32 v231, v10, v11
	v_cvt_pk_bf16_f32 v232, v4, v5
	v_cvt_pk_bf16_f32 v233, v6, v7
	v_cvt_pk_bf16_f32 v234, v0, v1
	v_cvt_pk_bf16_f32 v235, v2, v3
	v_add_u32_e32 v150, 0x58000, v112
	global_store_dwordx4 v150, v[228:231], s[42:43]
	global_store_dwordx4 v150, v[232:235], s[42:43] offset:256
.Lqkv_done:
	s_mov_b64 s[40:41], -1
	s_andn2_b64 vcc, exec, s[6:7]
	s_mov_b64 s[6:7], -1
	s_cbranch_vccnz .LBB0_2147
	s_branch .Lqkv_tail

.Lqkv_tail:
	s_andn2_b64 vcc, exec, s[18:19]
	s_cbranch_vccnz .LBB0_2146
	s_barrier
	s_branch .LBB0_2146
